# P3 q up-projection epilogue (rms scale + rope + pack) rewritten by hand: hoisted/overlapped ssq loads, trig only in rotating waves, batched bpermute, packed f32
# baseline (speedup 1.0000x reference)
.LBB0_837:
	s_cmp_gt_i32 s54, 15
	s_cselect_b32 s2, 1, 0
	s_lshl_b32 s54, s54, 8
	s_add_i32 s54, s54, s44
	s_lshl_b32 s6, s55, 8
	s_or_b32 s60, s6, s45
	v_or_b32_e32 v216, s54, v200
	v_mul_u32_u24_e32 v217, 0x90, v216
	v_add_u32_e32 v218, 0x1200, v217
	global_load_dwordx4 v[112:115], v217, s[12:13]
	global_load_dwordx4 v[116:119], v217, s[12:13] offset:16
	global_load_dwordx4 v[120:123], v217, s[12:13] offset:32
	global_load_dwordx4 v[132:135], v217, s[12:13] offset:2304
	global_load_dwordx4 v[136:139], v217, s[12:13] offset:2320
	global_load_dwordx4 v[140:143], v217, s[12:13] offset:2336
	global_load_dwordx4 v[152:155], v218, s[12:13]
	global_load_dwordx4 v[156:159], v218, s[12:13] offset:16
	global_load_dwordx4 v[160:163], v218, s[12:13] offset:32
	global_load_dwordx4 v[184:187], v218, s[12:13] offset:2304
	global_load_dwordx4 v[188:191], v218, s[12:13] offset:2320
	global_load_dwordx4 v[192:195], v218, s[12:13] offset:2336
	s_mul_hi_i32 s6, s60, 0x2aaaaaab
	s_lshr_b32 s7, s6, 31
	s_lshr_b32 s6, s6, 4
	s_add_i32 s6, s6, s7
	s_mulk_i32 s6, 0x60
	s_sub_i32 s6, s60, s6
	s_cmp_eq_u32 s6, 64
	s_cselect_b32 s61, 1, 0
	s_and_b32 s61, s61, s2
	s_or_b32 s8, s60, 0x80
	s_mul_hi_i32 s6, s8, 0x2aaaaaab
	s_lshr_b32 s7, s6, 31
	s_lshr_b32 s6, s6, 4
	s_add_i32 s6, s6, s7
	s_mulk_i32 s6, 0x60
	s_sub_i32 s6, s8, s6
	s_cmp_eq_u32 s6, 64
	s_cselect_b32 s62, 1, 0
	s_and_b32 s62, s62, s2
	s_bfe_u32 s55, s54, 0x40006
	v_xor_b32_e32 v213, 16, v209
	v_lshlrev_b32_e32 v213, 2, v213
	v_mul_u32_u24_e32 v211, 0x600, v216
	s_lshl_b32 s6, s60, 1
	v_add3_u32 v211, v211, v172, s6
	v_add_u32_e32 v217, 0x4800, v217
	v_add_u32_e32 v218, 0x4800, v218
	s_waitcnt vmcnt(0)
	v_pk_add_f32 v[112:113], v[112:113], v[114:115]
	v_pk_add_f32 v[116:117], v[116:117], v[118:119]
	v_pk_add_f32 v[120:121], v[120:121], v[122:123]
	v_pk_add_f32 v[112:113], v[112:113], v[116:117]
	v_pk_add_f32 v[112:113], v[112:113], v[120:121]
	v_add_f32_e32 v112, v112, v113
	v_fmamk_f32 v112, v112, 0x3b2aaaab, v208
	v_pk_add_f32 v[132:133], v[132:133], v[134:135]
	v_pk_add_f32 v[136:137], v[136:137], v[138:139]
	v_pk_add_f32 v[140:141], v[140:141], v[142:143]
	v_pk_add_f32 v[132:133], v[132:133], v[136:137]
	v_pk_add_f32 v[132:133], v[132:133], v[140:141]
	v_add_f32_e32 v132, v132, v133
	v_fmamk_f32 v132, v132, 0x3b2aaaab, v208
	v_pk_add_f32 v[152:153], v[152:153], v[154:155]
	v_pk_add_f32 v[156:157], v[156:157], v[158:159]
	v_pk_add_f32 v[160:161], v[160:161], v[162:163]
	v_pk_add_f32 v[152:153], v[152:153], v[156:157]
	v_pk_add_f32 v[152:153], v[152:153], v[160:161]
	v_add_f32_e32 v152, v152, v153
	v_fmamk_f32 v152, v152, 0x3b2aaaab, v208
	v_pk_add_f32 v[184:185], v[184:185], v[186:187]
	v_pk_add_f32 v[188:189], v[188:189], v[190:191]
	v_pk_add_f32 v[192:193], v[192:193], v[194:195]
	v_pk_add_f32 v[184:185], v[184:185], v[188:189]
	v_pk_add_f32 v[184:185], v[184:185], v[192:193]
	v_add_f32_e32 v184, v184, v185
	v_fmamk_f32 v184, v184, 0x3b2aaaab, v208
	v_rsq_f32_e32 v196, v112
	v_rsq_f32_e32 v198, v132
	v_rsq_f32_e32 v210, v152
	v_rsq_f32_e32 v212, v184
	s_nop 0
	v_mul_f32_e32 v196, 0x3e16c740, v196
	v_mul_f32_e32 v198, 0x3e16c740, v198
	v_mul_f32_e32 v210, 0x3e16c740, v210
	v_mul_f32_e32 v212, 0x3e16c740, v212
	global_load_dwordx4 v[112:115], v217, s[12:13]
	global_load_dwordx4 v[116:119], v217, s[12:13] offset:16
	global_load_dwordx4 v[120:123], v217, s[12:13] offset:32
	global_load_dwordx4 v[132:135], v217, s[12:13] offset:2304
	global_load_dwordx4 v[136:139], v217, s[12:13] offset:2320
	global_load_dwordx4 v[140:143], v217, s[12:13] offset:2336
	global_load_dwordx4 v[152:155], v218, s[12:13]
	global_load_dwordx4 v[156:159], v218, s[12:13] offset:16
	global_load_dwordx4 v[160:163], v218, s[12:13] offset:32
	global_load_dwordx4 v[184:187], v218, s[12:13] offset:2304
	global_load_dwordx4 v[188:191], v218, s[12:13] offset:2320
	global_load_dwordx4 v[192:195], v218, s[12:13] offset:2336
	v_pk_mul_f32 v[148:149], v[148:149], v[196:197] op_sel_hi:[1,0]
	v_pk_mul_f32 v[150:151], v[150:151], v[196:197] op_sel_hi:[1,0]
	v_pk_mul_f32 v[144:145], v[144:145], v[196:197] op_sel_hi:[1,0]
	v_pk_mul_f32 v[146:147], v[146:147], v[196:197] op_sel_hi:[1,0]
	s_cmp_eq_u32 s61, 0
	s_cbranch_scc1 .Lq2_000
	v_mov_b32_e32 v199, s55
	v_cndmask_b32_e64 v199, v200, v199, s[10:11]
	v_cvt_f32_ubyte0_e32 v199, v199
	v_mul_f32_e32 v199, v174, v199
	ds_bpermute_b32 v216, v213, v148
	ds_bpermute_b32 v217, v213, v149
	ds_bpermute_b32 v218, v213, v150
	ds_bpermute_b32 v219, v213, v151
	v_mul_f32_e32 v220, 0x3e22f983, v199
	v_mul_f32_e32 v221, 0x3d4e2601, v199
	v_mul_f32_e32 v222, 0x3c826136, v199
	v_mul_f32_e32 v223, 0x3ba4eb34, v199
	v_cos_f32_e32 v224, v220
	v_cos_f32_e32 v225, v221
	v_cos_f32_e32 v226, v222
	v_cos_f32_e32 v227, v223
	v_sin_f32_e32 v220, v220
	v_sin_f32_e32 v221, v221
	v_sin_f32_e32 v222, v222
	v_sin_f32_e32 v223, v223
	s_waitcnt lgkmcnt(0)
	v_pk_mul_f32 v[216:217], v[216:217], v[220:221]
	v_pk_mul_f32 v[218:219], v[218:219], v[222:223]
	v_pk_fma_f32 v[148:149], v[148:149], v[224:225], v[216:217]
	v_pk_fma_f32 v[150:151], v[150:151], v[226:227], v[218:219]
	ds_bpermute_b32 v216, v213, v144
	ds_bpermute_b32 v217, v213, v145
	ds_bpermute_b32 v218, v213, v146
	ds_bpermute_b32 v219, v213, v147
	v_mul_f32_e32 v220, 0x3ad09b8a, v199
	v_mul_f32_e32 v221, 0x3a03ef5d, v199
	v_mul_f32_e32 v222, 0x3926e2d4, v199
	v_mul_f32_e32 v223, 0x38531894, v199
	v_cos_f32_e32 v224, v220
	v_cos_f32_e32 v225, v221
	v_cos_f32_e32 v226, v222
	v_cos_f32_e32 v227, v223
	v_sin_f32_e32 v220, v220
	v_sin_f32_e32 v221, v221
	v_sin_f32_e32 v222, v222
	v_sin_f32_e32 v223, v223
	s_waitcnt lgkmcnt(0)
	v_pk_mul_f32 v[216:217], v[216:217], v[220:221]
	v_pk_mul_f32 v[218:219], v[218:219], v[222:223]
	v_pk_fma_f32 v[144:145], v[144:145], v[224:225], v[216:217]
	v_pk_fma_f32 v[146:147], v[146:147], v[226:227], v[218:219]
.Lq2_000:
	v_cvt_pk_bf16_f32 v148, v148, v149
	v_cvt_pk_bf16_f32 v149, v150, v151
	v_cvt_pk_bf16_f32 v150, v144, v145
	v_cvt_pk_bf16_f32 v151, v146, v147
	global_store_dwordx4 v211, v[148:151], s[16:17]
	v_pk_mul_f32 v[128:129], v[128:129], v[196:197] op_sel_hi:[1,0]
	v_pk_mul_f32 v[130:131], v[130:131], v[196:197] op_sel_hi:[1,0]
	v_pk_mul_f32 v[124:125], v[124:125], v[196:197] op_sel_hi:[1,0]
	v_pk_mul_f32 v[126:127], v[126:127], v[196:197] op_sel_hi:[1,0]
	s_cmp_eq_u32 s62, 0
	s_cbranch_scc1 .Lq2_001
	v_mov_b32_e32 v199, s55
	v_cndmask_b32_e64 v199, v200, v199, s[10:11]
	v_cvt_f32_ubyte0_e32 v199, v199
	v_mul_f32_e32 v199, v174, v199
	ds_bpermute_b32 v216, v213, v128
	ds_bpermute_b32 v217, v213, v129
	ds_bpermute_b32 v218, v213, v130
	ds_bpermute_b32 v219, v213, v131
	v_mul_f32_e32 v220, 0x3e22f983, v199
	v_mul_f32_e32 v221, 0x3d4e2601, v199
	v_mul_f32_e32 v222, 0x3c826136, v199
	v_mul_f32_e32 v223, 0x3ba4eb34, v199
	v_cos_f32_e32 v224, v220
	v_cos_f32_e32 v225, v221
	v_cos_f32_e32 v226, v222
	v_cos_f32_e32 v227, v223
	v_sin_f32_e32 v220, v220
	v_sin_f32_e32 v221, v221
	v_sin_f32_e32 v222, v222
	v_sin_f32_e32 v223, v223
	s_waitcnt lgkmcnt(0)
	v_pk_mul_f32 v[216:217], v[216:217], v[220:221]
	v_pk_mul_f32 v[218:219], v[218:219], v[222:223]
	v_pk_fma_f32 v[128:129], v[128:129], v[224:225], v[216:217]
	v_pk_fma_f32 v[130:131], v[130:131], v[226:227], v[218:219]
	ds_bpermute_b32 v216, v213, v124
	ds_bpermute_b32 v217, v213, v125
	ds_bpermute_b32 v218, v213, v126
	ds_bpermute_b32 v219, v213, v127
	v_mul_f32_e32 v220, 0x3ad09b8a, v199
	v_mul_f32_e32 v221, 0x3a03ef5d, v199
	v_mul_f32_e32 v222, 0x3926e2d4, v199
	v_mul_f32_e32 v223, 0x38531894, v199
	v_cos_f32_e32 v224, v220
	v_cos_f32_e32 v225, v221
	v_cos_f32_e32 v226, v222
	v_cos_f32_e32 v227, v223
	v_sin_f32_e32 v220, v220
	v_sin_f32_e32 v221, v221
	v_sin_f32_e32 v222, v222
	v_sin_f32_e32 v223, v223
	s_waitcnt lgkmcnt(0)
	v_pk_mul_f32 v[216:217], v[216:217], v[220:221]
	v_pk_mul_f32 v[218:219], v[218:219], v[222:223]
	v_pk_fma_f32 v[124:125], v[124:125], v[224:225], v[216:217]
	v_pk_fma_f32 v[126:127], v[126:127], v[226:227], v[218:219]
.Lq2_001:
	v_cvt_pk_bf16_f32 v128, v128, v129
	v_cvt_pk_bf16_f32 v129, v130, v131
	v_cvt_pk_bf16_f32 v130, v124, v125
	v_cvt_pk_bf16_f32 v131, v126, v127
	global_store_dwordx4 v211, v[128:131], s[16:17] offset:256
	v_add_u32_e32 v197, 0x6000, v211
	v_pk_mul_f32 v[108:109], v[108:109], v[198:199] op_sel_hi:[1,0]
	v_pk_mul_f32 v[110:111], v[110:111], v[198:199] op_sel_hi:[1,0]
	v_pk_mul_f32 v[104:105], v[104:105], v[198:199] op_sel_hi:[1,0]
	v_pk_mul_f32 v[106:107], v[106:107], v[198:199] op_sel_hi:[1,0]
	s_cmp_eq_u32 s61, 0
	s_cbranch_scc1 .Lq2_010
	v_mov_b32_e32 v199, s55
	v_cndmask_b32_e64 v199, v202, v199, s[10:11]
	v_cvt_f32_ubyte0_e32 v199, v199
	v_mul_f32_e32 v199, v174, v199
	ds_bpermute_b32 v216, v213, v108
	ds_bpermute_b32 v217, v213, v109
	ds_bpermute_b32 v218, v213, v110
	ds_bpermute_b32 v219, v213, v111
	v_mul_f32_e32 v220, 0x3e22f983, v199
	v_mul_f32_e32 v221, 0x3d4e2601, v199
	v_mul_f32_e32 v222, 0x3c826136, v199
	v_mul_f32_e32 v223, 0x3ba4eb34, v199
	v_cos_f32_e32 v224, v220
	v_cos_f32_e32 v225, v221
	v_cos_f32_e32 v226, v222
	v_cos_f32_e32 v227, v223
	v_sin_f32_e32 v220, v220
	v_sin_f32_e32 v221, v221
	v_sin_f32_e32 v222, v222
	v_sin_f32_e32 v223, v223
	s_waitcnt lgkmcnt(0)
	v_pk_mul_f32 v[216:217], v[216:217], v[220:221]
	v_pk_mul_f32 v[218:219], v[218:219], v[222:223]
	v_pk_fma_f32 v[108:109], v[108:109], v[224:225], v[216:217]
	v_pk_fma_f32 v[110:111], v[110:111], v[226:227], v[218:219]
	ds_bpermute_b32 v216, v213, v104
	ds_bpermute_b32 v217, v213, v105
	ds_bpermute_b32 v218, v213, v106
	ds_bpermute_b32 v219, v213, v107
	v_mul_f32_e32 v220, 0x3ad09b8a, v199
	v_mul_f32_e32 v221, 0x3a03ef5d, v199
	v_mul_f32_e32 v222, 0x3926e2d4, v199
	v_mul_f32_e32 v223, 0x38531894, v199
	v_cos_f32_e32 v224, v220
	v_cos_f32_e32 v225, v221
	v_cos_f32_e32 v226, v222
	v_cos_f32_e32 v227, v223
	v_sin_f32_e32 v220, v220
	v_sin_f32_e32 v221, v221
	v_sin_f32_e32 v222, v222
	v_sin_f32_e32 v223, v223
	s_waitcnt lgkmcnt(0)
	v_pk_mul_f32 v[216:217], v[216:217], v[220:221]
	v_pk_mul_f32 v[218:219], v[218:219], v[222:223]
	v_pk_fma_f32 v[104:105], v[104:105], v[224:225], v[216:217]
	v_pk_fma_f32 v[106:107], v[106:107], v[226:227], v[218:219]
.Lq2_010:
	v_cvt_pk_bf16_f32 v108, v108, v109
	v_cvt_pk_bf16_f32 v109, v110, v111
	v_cvt_pk_bf16_f32 v110, v104, v105
	v_cvt_pk_bf16_f32 v111, v106, v107
	global_store_dwordx4 v197, v[108:111], s[16:17]
	v_pk_mul_f32 v[100:101], v[100:101], v[198:199] op_sel_hi:[1,0]
	v_pk_mul_f32 v[102:103], v[102:103], v[198:199] op_sel_hi:[1,0]
	v_pk_mul_f32 v[96:97], v[96:97], v[198:199] op_sel_hi:[1,0]
	v_pk_mul_f32 v[98:99], v[98:99], v[198:199] op_sel_hi:[1,0]
	s_cmp_eq_u32 s62, 0
	s_cbranch_scc1 .Lq2_011
	v_mov_b32_e32 v199, s55
	v_cndmask_b32_e64 v199, v202, v199, s[10:11]
	v_cvt_f32_ubyte0_e32 v199, v199
	v_mul_f32_e32 v199, v174, v199
	ds_bpermute_b32 v216, v213, v100
	ds_bpermute_b32 v217, v213, v101
	ds_bpermute_b32 v218, v213, v102
	ds_bpermute_b32 v219, v213, v103
	v_mul_f32_e32 v220, 0x3e22f983, v199
	v_mul_f32_e32 v221, 0x3d4e2601, v199
	v_mul_f32_e32 v222, 0x3c826136, v199
	v_mul_f32_e32 v223, 0x3ba4eb34, v199
	v_cos_f32_e32 v224, v220
	v_cos_f32_e32 v225, v221
	v_cos_f32_e32 v226, v222
	v_cos_f32_e32 v227, v223
	v_sin_f32_e32 v220, v220
	v_sin_f32_e32 v221, v221
	v_sin_f32_e32 v222, v222
	v_sin_f32_e32 v223, v223
	s_waitcnt lgkmcnt(0)
	v_pk_mul_f32 v[216:217], v[216:217], v[220:221]
	v_pk_mul_f32 v[218:219], v[218:219], v[222:223]
	v_pk_fma_f32 v[100:101], v[100:101], v[224:225], v[216:217]
	v_pk_fma_f32 v[102:103], v[102:103], v[226:227], v[218:219]
	ds_bpermute_b32 v216, v213, v96
	ds_bpermute_b32 v217, v213, v97
	ds_bpermute_b32 v218, v213, v98
	ds_bpermute_b32 v219, v213, v99
	v_mul_f32_e32 v220, 0x3ad09b8a, v199
	v_mul_f32_e32 v221, 0x3a03ef5d, v199
	v_mul_f32_e32 v222, 0x3926e2d4, v199
	v_mul_f32_e32 v223, 0x38531894, v199
	v_cos_f32_e32 v224, v220
	v_cos_f32_e32 v225, v221
	v_cos_f32_e32 v226, v222
	v_cos_f32_e32 v227, v223
	v_sin_f32_e32 v220, v220
	v_sin_f32_e32 v221, v221
	v_sin_f32_e32 v222, v222
	v_sin_f32_e32 v223, v223
	s_waitcnt lgkmcnt(0)
	v_pk_mul_f32 v[216:217], v[216:217], v[220:221]
	v_pk_mul_f32 v[218:219], v[218:219], v[222:223]
	v_pk_fma_f32 v[96:97], v[96:97], v[224:225], v[216:217]
	v_pk_fma_f32 v[98:99], v[98:99], v[226:227], v[218:219]
.Lq2_011:
	v_cvt_pk_bf16_f32 v100, v100, v101
	v_cvt_pk_bf16_f32 v101, v102, v103
	v_cvt_pk_bf16_f32 v102, v96, v97
	v_cvt_pk_bf16_f32 v103, v98, v99
	global_store_dwordx4 v197, v[100:103], s[16:17] offset:256
	v_add_u32_e32 v197, 0xc000, v211
	v_pk_mul_f32 v[92:93], v[92:93], v[210:211] op_sel_hi:[1,0]
	v_pk_mul_f32 v[94:95], v[94:95], v[210:211] op_sel_hi:[1,0]
	v_pk_mul_f32 v[88:89], v[88:89], v[210:211] op_sel_hi:[1,0]
	v_pk_mul_f32 v[90:91], v[90:91], v[210:211] op_sel_hi:[1,0]
	s_cmp_eq_u32 s61, 0
	s_cbranch_scc1 .Lq2_020
	v_mov_b32_e32 v199, s55
	v_cndmask_b32_e64 v199, v203, v199, s[10:11]
	v_cvt_f32_ubyte0_e32 v199, v199
	v_mul_f32_e32 v199, v174, v199
	ds_bpermute_b32 v216, v213, v92
	ds_bpermute_b32 v217, v213, v93
	ds_bpermute_b32 v218, v213, v94
	ds_bpermute_b32 v219, v213, v95
	v_mul_f32_e32 v220, 0x3e22f983, v199
	v_mul_f32_e32 v221, 0x3d4e2601, v199
	v_mul_f32_e32 v222, 0x3c826136, v199
	v_mul_f32_e32 v223, 0x3ba4eb34, v199
	v_cos_f32_e32 v224, v220
	v_cos_f32_e32 v225, v221
	v_cos_f32_e32 v226, v222
	v_cos_f32_e32 v227, v223
	v_sin_f32_e32 v220, v220
	v_sin_f32_e32 v221, v221
	v_sin_f32_e32 v222, v222
	v_sin_f32_e32 v223, v223
	s_waitcnt lgkmcnt(0)
	v_pk_mul_f32 v[216:217], v[216:217], v[220:221]
	v_pk_mul_f32 v[218:219], v[218:219], v[222:223]
	v_pk_fma_f32 v[92:93], v[92:93], v[224:225], v[216:217]
	v_pk_fma_f32 v[94:95], v[94:95], v[226:227], v[218:219]
	ds_bpermute_b32 v216, v213, v88
	ds_bpermute_b32 v217, v213, v89
	ds_bpermute_b32 v218, v213, v90
	ds_bpermute_b32 v219, v213, v91
	v_mul_f32_e32 v220, 0x3ad09b8a, v199
	v_mul_f32_e32 v221, 0x3a03ef5d, v199
	v_mul_f32_e32 v222, 0x3926e2d4, v199
	v_mul_f32_e32 v223, 0x38531894, v199
	v_cos_f32_e32 v224, v220
	v_cos_f32_e32 v225, v221
	v_cos_f32_e32 v226, v222
	v_cos_f32_e32 v227, v223
	v_sin_f32_e32 v220, v220
	v_sin_f32_e32 v221, v221
	v_sin_f32_e32 v222, v222
	v_sin_f32_e32 v223, v223
	s_waitcnt lgkmcnt(0)
	v_pk_mul_f32 v[216:217], v[216:217], v[220:221]
	v_pk_mul_f32 v[218:219], v[218:219], v[222:223]
	v_pk_fma_f32 v[88:89], v[88:89], v[224:225], v[216:217]
	v_pk_fma_f32 v[90:91], v[90:91], v[226:227], v[218:219]
.Lq2_020:
	v_cvt_pk_bf16_f32 v92, v92, v93
	v_cvt_pk_bf16_f32 v93, v94, v95
	v_cvt_pk_bf16_f32 v94, v88, v89
	v_cvt_pk_bf16_f32 v95, v90, v91
	global_store_dwordx4 v197, v[92:95], s[16:17]
	v_pk_mul_f32 v[84:85], v[84:85], v[210:211] op_sel_hi:[1,0]
	v_pk_mul_f32 v[86:87], v[86:87], v[210:211] op_sel_hi:[1,0]
	v_pk_mul_f32 v[80:81], v[80:81], v[210:211] op_sel_hi:[1,0]
	v_pk_mul_f32 v[82:83], v[82:83], v[210:211] op_sel_hi:[1,0]
	s_cmp_eq_u32 s62, 0
	s_cbranch_scc1 .Lq2_021
	v_mov_b32_e32 v199, s55
	v_cndmask_b32_e64 v199, v203, v199, s[10:11]
	v_cvt_f32_ubyte0_e32 v199, v199
	v_mul_f32_e32 v199, v174, v199
	ds_bpermute_b32 v216, v213, v84
	ds_bpermute_b32 v217, v213, v85
	ds_bpermute_b32 v218, v213, v86
	ds_bpermute_b32 v219, v213, v87
	v_mul_f32_e32 v220, 0x3e22f983, v199
	v_mul_f32_e32 v221, 0x3d4e2601, v199
	v_mul_f32_e32 v222, 0x3c826136, v199
	v_mul_f32_e32 v223, 0x3ba4eb34, v199
	v_cos_f32_e32 v224, v220
	v_cos_f32_e32 v225, v221
	v_cos_f32_e32 v226, v222
	v_cos_f32_e32 v227, v223
	v_sin_f32_e32 v220, v220
	v_sin_f32_e32 v221, v221
	v_sin_f32_e32 v222, v222
	v_sin_f32_e32 v223, v223
	s_waitcnt lgkmcnt(0)
	v_pk_mul_f32 v[216:217], v[216:217], v[220:221]
	v_pk_mul_f32 v[218:219], v[218:219], v[222:223]
	v_pk_fma_f32 v[84:85], v[84:85], v[224:225], v[216:217]
	v_pk_fma_f32 v[86:87], v[86:87], v[226:227], v[218:219]
	ds_bpermute_b32 v216, v213, v80
	ds_bpermute_b32 v217, v213, v81
	ds_bpermute_b32 v218, v213, v82
	ds_bpermute_b32 v219, v213, v83
	v_mul_f32_e32 v220, 0x3ad09b8a, v199
	v_mul_f32_e32 v221, 0x3a03ef5d, v199
	v_mul_f32_e32 v222, 0x3926e2d4, v199
	v_mul_f32_e32 v223, 0x38531894, v199
	v_cos_f32_e32 v224, v220
	v_cos_f32_e32 v225, v221
	v_cos_f32_e32 v226, v222
	v_cos_f32_e32 v227, v223
	v_sin_f32_e32 v220, v220
	v_sin_f32_e32 v221, v221
	v_sin_f32_e32 v222, v222
	v_sin_f32_e32 v223, v223
	s_waitcnt lgkmcnt(0)
	v_pk_mul_f32 v[216:217], v[216:217], v[220:221]
	v_pk_mul_f32 v[218:219], v[218:219], v[222:223]
	v_pk_fma_f32 v[80:81], v[80:81], v[224:225], v[216:217]
	v_pk_fma_f32 v[82:83], v[82:83], v[226:227], v[218:219]
.Lq2_021:
	v_cvt_pk_bf16_f32 v84, v84, v85
	v_cvt_pk_bf16_f32 v85, v86, v87
	v_cvt_pk_bf16_f32 v86, v80, v81
	v_cvt_pk_bf16_f32 v87, v82, v83
	global_store_dwordx4 v197, v[84:87], s[16:17] offset:256
	v_add_u32_e32 v197, 0x12000, v211
	v_pk_mul_f32 v[76:77], v[76:77], v[212:213] op_sel_hi:[1,0]
	v_pk_mul_f32 v[78:79], v[78:79], v[212:213] op_sel_hi:[1,0]
	v_pk_mul_f32 v[72:73], v[72:73], v[212:213] op_sel_hi:[1,0]
	v_pk_mul_f32 v[74:75], v[74:75], v[212:213] op_sel_hi:[1,0]
	s_cmp_eq_u32 s61, 0
	s_cbranch_scc1 .Lq2_030
	v_mov_b32_e32 v199, s55
	v_cndmask_b32_e64 v199, v204, v199, s[10:11]
	v_cvt_f32_ubyte0_e32 v199, v199
	v_mul_f32_e32 v199, v174, v199
	ds_bpermute_b32 v216, v213, v76
	ds_bpermute_b32 v217, v213, v77
	ds_bpermute_b32 v218, v213, v78
	ds_bpermute_b32 v219, v213, v79
	v_mul_f32_e32 v220, 0x3e22f983, v199
	v_mul_f32_e32 v221, 0x3d4e2601, v199
	v_mul_f32_e32 v222, 0x3c826136, v199
	v_mul_f32_e32 v223, 0x3ba4eb34, v199
	v_cos_f32_e32 v224, v220
	v_cos_f32_e32 v225, v221
	v_cos_f32_e32 v226, v222
	v_cos_f32_e32 v227, v223
	v_sin_f32_e32 v220, v220
	v_sin_f32_e32 v221, v221
	v_sin_f32_e32 v222, v222
	v_sin_f32_e32 v223, v223
	s_waitcnt lgkmcnt(0)
	v_pk_mul_f32 v[216:217], v[216:217], v[220:221]
	v_pk_mul_f32 v[218:219], v[218:219], v[222:223]
	v_pk_fma_f32 v[76:77], v[76:77], v[224:225], v[216:217]
	v_pk_fma_f32 v[78:79], v[78:79], v[226:227], v[218:219]
	ds_bpermute_b32 v216, v213, v72
	ds_bpermute_b32 v217, v213, v73
	ds_bpermute_b32 v218, v213, v74
	ds_bpermute_b32 v219, v213, v75
	v_mul_f32_e32 v220, 0x3ad09b8a, v199
	v_mul_f32_e32 v221, 0x3a03ef5d, v199
	v_mul_f32_e32 v222, 0x3926e2d4, v199
	v_mul_f32_e32 v223, 0x38531894, v199
	v_cos_f32_e32 v224, v220
	v_cos_f32_e32 v225, v221
	v_cos_f32_e32 v226, v222
	v_cos_f32_e32 v227, v223
	v_sin_f32_e32 v220, v220
	v_sin_f32_e32 v221, v221
	v_sin_f32_e32 v222, v222
	v_sin_f32_e32 v223, v223
	s_waitcnt lgkmcnt(0)
	v_pk_mul_f32 v[216:217], v[216:217], v[220:221]
	v_pk_mul_f32 v[218:219], v[218:219], v[222:223]
	v_pk_fma_f32 v[72:73], v[72:73], v[224:225], v[216:217]
	v_pk_fma_f32 v[74:75], v[74:75], v[226:227], v[218:219]
.Lq2_030:
	v_cvt_pk_bf16_f32 v76, v76, v77
	v_cvt_pk_bf16_f32 v77, v78, v79
	v_cvt_pk_bf16_f32 v78, v72, v73
	v_cvt_pk_bf16_f32 v79, v74, v75
	global_store_dwordx4 v197, v[76:79], s[16:17]
	v_pk_mul_f32 v[68:69], v[68:69], v[212:213] op_sel_hi:[1,0]
	v_pk_mul_f32 v[70:71], v[70:71], v[212:213] op_sel_hi:[1,0]
	v_pk_mul_f32 v[64:65], v[64:65], v[212:213] op_sel_hi:[1,0]
	v_pk_mul_f32 v[66:67], v[66:67], v[212:213] op_sel_hi:[1,0]
	s_cmp_eq_u32 s62, 0
	s_cbranch_scc1 .Lq2_031
	v_mov_b32_e32 v199, s55
	v_cndmask_b32_e64 v199, v204, v199, s[10:11]
	v_cvt_f32_ubyte0_e32 v199, v199
	v_mul_f32_e32 v199, v174, v199
	ds_bpermute_b32 v216, v213, v68
	ds_bpermute_b32 v217, v213, v69
	ds_bpermute_b32 v218, v213, v70
	ds_bpermute_b32 v219, v213, v71
	v_mul_f32_e32 v220, 0x3e22f983, v199
	v_mul_f32_e32 v221, 0x3d4e2601, v199
	v_mul_f32_e32 v222, 0x3c826136, v199
	v_mul_f32_e32 v223, 0x3ba4eb34, v199
	v_cos_f32_e32 v224, v220
	v_cos_f32_e32 v225, v221
	v_cos_f32_e32 v226, v222
	v_cos_f32_e32 v227, v223
	v_sin_f32_e32 v220, v220
	v_sin_f32_e32 v221, v221
	v_sin_f32_e32 v222, v222
	v_sin_f32_e32 v223, v223
	s_waitcnt lgkmcnt(0)
	v_pk_mul_f32 v[216:217], v[216:217], v[220:221]
	v_pk_mul_f32 v[218:219], v[218:219], v[222:223]
	v_pk_fma_f32 v[68:69], v[68:69], v[224:225], v[216:217]
	v_pk_fma_f32 v[70:71], v[70:71], v[226:227], v[218:219]
	ds_bpermute_b32 v216, v213, v64
	ds_bpermute_b32 v217, v213, v65
	ds_bpermute_b32 v218, v213, v66
	ds_bpermute_b32 v219, v213, v67
	v_mul_f32_e32 v220, 0x3ad09b8a, v199
	v_mul_f32_e32 v221, 0x3a03ef5d, v199
	v_mul_f32_e32 v222, 0x3926e2d4, v199
	v_mul_f32_e32 v223, 0x38531894, v199
	v_cos_f32_e32 v224, v220
	v_cos_f32_e32 v225, v221
	v_cos_f32_e32 v226, v222
	v_cos_f32_e32 v227, v223
	v_sin_f32_e32 v220, v220
	v_sin_f32_e32 v221, v221
	v_sin_f32_e32 v222, v222
	v_sin_f32_e32 v223, v223
	s_waitcnt lgkmcnt(0)
	v_pk_mul_f32 v[216:217], v[216:217], v[220:221]
	v_pk_mul_f32 v[218:219], v[218:219], v[222:223]
	v_pk_fma_f32 v[64:65], v[64:65], v[224:225], v[216:217]
	v_pk_fma_f32 v[66:67], v[66:67], v[226:227], v[218:219]
.Lq2_031:
	v_cvt_pk_bf16_f32 v68, v68, v69
	v_cvt_pk_bf16_f32 v69, v70, v71
	v_cvt_pk_bf16_f32 v70, v64, v65
	v_cvt_pk_bf16_f32 v71, v66, v67
	global_store_dwordx4 v197, v[68:71], s[16:17] offset:256
	s_add_i32 s6, s54, 0x80
	s_bfe_u32 s55, s6, 0x40006
	s_waitcnt vmcnt(8)
	v_pk_add_f32 v[112:113], v[112:113], v[114:115]
	v_pk_add_f32 v[116:117], v[116:117], v[118:119]
	v_pk_add_f32 v[120:121], v[120:121], v[122:123]
	v_pk_add_f32 v[112:113], v[112:113], v[116:117]
	v_pk_add_f32 v[112:113], v[112:113], v[120:121]
	v_add_f32_e32 v112, v112, v113
	v_fmamk_f32 v112, v112, 0x3b2aaaab, v208
	v_pk_add_f32 v[132:133], v[132:133], v[134:135]
	v_pk_add_f32 v[136:137], v[136:137], v[138:139]
	v_pk_add_f32 v[140:141], v[140:141], v[142:143]
	v_pk_add_f32 v[132:133], v[132:133], v[136:137]
	v_pk_add_f32 v[132:133], v[132:133], v[140:141]
	v_add_f32_e32 v132, v132, v133
	v_fmamk_f32 v132, v132, 0x3b2aaaab, v208
	v_pk_add_f32 v[152:153], v[152:153], v[154:155]
	v_pk_add_f32 v[156:157], v[156:157], v[158:159]
	v_pk_add_f32 v[160:161], v[160:161], v[162:163]
	v_pk_add_f32 v[152:153], v[152:153], v[156:157]
	v_pk_add_f32 v[152:153], v[152:153], v[160:161]
	v_add_f32_e32 v152, v152, v153
	v_fmamk_f32 v152, v152, 0x3b2aaaab, v208
	v_pk_add_f32 v[184:185], v[184:185], v[186:187]
	v_pk_add_f32 v[188:189], v[188:189], v[190:191]
	v_pk_add_f32 v[192:193], v[192:193], v[194:195]
	v_pk_add_f32 v[184:185], v[184:185], v[188:189]
	v_pk_add_f32 v[184:185], v[184:185], v[192:193]
	v_add_f32_e32 v184, v184, v185
	v_fmamk_f32 v184, v184, 0x3b2aaaab, v208
	v_rsq_f32_e32 v196, v112
	v_rsq_f32_e32 v198, v132
	v_rsq_f32_e32 v210, v152
	v_rsq_f32_e32 v212, v184
	s_nop 0
	v_mul_f32_e32 v196, 0x3e16c740, v196
	v_mul_f32_e32 v198, 0x3e16c740, v198
	v_mul_f32_e32 v210, 0x3e16c740, v210
	v_mul_f32_e32 v212, 0x3e16c740, v212
	v_add_u32_e32 v197, 0x30000, v211
	v_pk_mul_f32 v[60:61], v[60:61], v[196:197] op_sel_hi:[1,0]
	v_pk_mul_f32 v[62:63], v[62:63], v[196:197] op_sel_hi:[1,0]
	v_pk_mul_f32 v[56:57], v[56:57], v[196:197] op_sel_hi:[1,0]
	v_pk_mul_f32 v[58:59], v[58:59], v[196:197] op_sel_hi:[1,0]
	s_cmp_eq_u32 s61, 0
	s_cbranch_scc1 .Lq2_100
	v_mov_b32_e32 v199, s55
	v_cndmask_b32_e64 v199, v200, v199, s[10:11]
	v_cvt_f32_ubyte0_e32 v199, v199
	v_mul_f32_e32 v199, v174, v199
	ds_bpermute_b32 v216, v213, v60
	ds_bpermute_b32 v217, v213, v61
	ds_bpermute_b32 v218, v213, v62
	ds_bpermute_b32 v219, v213, v63
	v_mul_f32_e32 v220, 0x3e22f983, v199
	v_mul_f32_e32 v221, 0x3d4e2601, v199
	v_mul_f32_e32 v222, 0x3c826136, v199
	v_mul_f32_e32 v223, 0x3ba4eb34, v199
	v_cos_f32_e32 v224, v220
	v_cos_f32_e32 v225, v221
	v_cos_f32_e32 v226, v222
	v_cos_f32_e32 v227, v223
	v_sin_f32_e32 v220, v220
	v_sin_f32_e32 v221, v221
	v_sin_f32_e32 v222, v222
	v_sin_f32_e32 v223, v223
	s_waitcnt lgkmcnt(0)
	v_pk_mul_f32 v[216:217], v[216:217], v[220:221]
	v_pk_mul_f32 v[218:219], v[218:219], v[222:223]
	v_pk_fma_f32 v[60:61], v[60:61], v[224:225], v[216:217]
	v_pk_fma_f32 v[62:63], v[62:63], v[226:227], v[218:219]
	ds_bpermute_b32 v216, v213, v56
	ds_bpermute_b32 v217, v213, v57
	ds_bpermute_b32 v218, v213, v58
	ds_bpermute_b32 v219, v213, v59
	v_mul_f32_e32 v220, 0x3ad09b8a, v199
	v_mul_f32_e32 v221, 0x3a03ef5d, v199
	v_mul_f32_e32 v222, 0x3926e2d4, v199
	v_mul_f32_e32 v223, 0x38531894, v199
	v_cos_f32_e32 v224, v220
	v_cos_f32_e32 v225, v221
	v_cos_f32_e32 v226, v222
	v_cos_f32_e32 v227, v223
	v_sin_f32_e32 v220, v220
	v_sin_f32_e32 v221, v221
	v_sin_f32_e32 v222, v222
	v_sin_f32_e32 v223, v223
	s_waitcnt lgkmcnt(0)
	v_pk_mul_f32 v[216:217], v[216:217], v[220:221]
	v_pk_mul_f32 v[218:219], v[218:219], v[222:223]
	v_pk_fma_f32 v[56:57], v[56:57], v[224:225], v[216:217]
	v_pk_fma_f32 v[58:59], v[58:59], v[226:227], v[218:219]
.Lq2_100:
	v_cvt_pk_bf16_f32 v60, v60, v61
	v_cvt_pk_bf16_f32 v61, v62, v63
	v_cvt_pk_bf16_f32 v62, v56, v57
	v_cvt_pk_bf16_f32 v63, v58, v59
	global_store_dwordx4 v197, v[60:63], s[16:17]
	v_pk_mul_f32 v[52:53], v[52:53], v[196:197] op_sel_hi:[1,0]
	v_pk_mul_f32 v[54:55], v[54:55], v[196:197] op_sel_hi:[1,0]
	v_pk_mul_f32 v[48:49], v[48:49], v[196:197] op_sel_hi:[1,0]
	v_pk_mul_f32 v[50:51], v[50:51], v[196:197] op_sel_hi:[1,0]
	s_cmp_eq_u32 s62, 0
	s_cbranch_scc1 .Lq2_101
	v_mov_b32_e32 v199, s55
	v_cndmask_b32_e64 v199, v200, v199, s[10:11]
	v_cvt_f32_ubyte0_e32 v199, v199
	v_mul_f32_e32 v199, v174, v199
	ds_bpermute_b32 v216, v213, v52
	ds_bpermute_b32 v217, v213, v53
	ds_bpermute_b32 v218, v213, v54
	ds_bpermute_b32 v219, v213, v55
	v_mul_f32_e32 v220, 0x3e22f983, v199
	v_mul_f32_e32 v221, 0x3d4e2601, v199
	v_mul_f32_e32 v222, 0x3c826136, v199
	v_mul_f32_e32 v223, 0x3ba4eb34, v199
	v_cos_f32_e32 v224, v220
	v_cos_f32_e32 v225, v221
	v_cos_f32_e32 v226, v222
	v_cos_f32_e32 v227, v223
	v_sin_f32_e32 v220, v220
	v_sin_f32_e32 v221, v221
	v_sin_f32_e32 v222, v222
	v_sin_f32_e32 v223, v223
	s_waitcnt lgkmcnt(0)
	v_pk_mul_f32 v[216:217], v[216:217], v[220:221]
	v_pk_mul_f32 v[218:219], v[218:219], v[222:223]
	v_pk_fma_f32 v[52:53], v[52:53], v[224:225], v[216:217]
	v_pk_fma_f32 v[54:55], v[54:55], v[226:227], v[218:219]
	ds_bpermute_b32 v216, v213, v48
	ds_bpermute_b32 v217, v213, v49
	ds_bpermute_b32 v218, v213, v50
	ds_bpermute_b32 v219, v213, v51
	v_mul_f32_e32 v220, 0x3ad09b8a, v199
	v_mul_f32_e32 v221, 0x3a03ef5d, v199
	v_mul_f32_e32 v222, 0x3926e2d4, v199
	v_mul_f32_e32 v223, 0x38531894, v199
	v_cos_f32_e32 v224, v220
	v_cos_f32_e32 v225, v221
	v_cos_f32_e32 v226, v222
	v_cos_f32_e32 v227, v223
	v_sin_f32_e32 v220, v220
	v_sin_f32_e32 v221, v221
	v_sin_f32_e32 v222, v222
	v_sin_f32_e32 v223, v223
	s_waitcnt lgkmcnt(0)
	v_pk_mul_f32 v[216:217], v[216:217], v[220:221]
	v_pk_mul_f32 v[218:219], v[218:219], v[222:223]
	v_pk_fma_f32 v[48:49], v[48:49], v[224:225], v[216:217]
	v_pk_fma_f32 v[50:51], v[50:51], v[226:227], v[218:219]
.Lq2_101:
	v_cvt_pk_bf16_f32 v52, v52, v53
	v_cvt_pk_bf16_f32 v53, v54, v55
	v_cvt_pk_bf16_f32 v54, v48, v49
	v_cvt_pk_bf16_f32 v55, v50, v51
	global_store_dwordx4 v197, v[52:55], s[16:17] offset:256
	v_add_u32_e32 v197, 0x36000, v211
	v_pk_mul_f32 v[44:45], v[44:45], v[198:199] op_sel_hi:[1,0]
	v_pk_mul_f32 v[46:47], v[46:47], v[198:199] op_sel_hi:[1,0]
	v_pk_mul_f32 v[40:41], v[40:41], v[198:199] op_sel_hi:[1,0]
	v_pk_mul_f32 v[42:43], v[42:43], v[198:199] op_sel_hi:[1,0]
	s_cmp_eq_u32 s61, 0
	s_cbranch_scc1 .Lq2_110
	v_mov_b32_e32 v199, s55
	v_cndmask_b32_e64 v199, v202, v199, s[10:11]
	v_cvt_f32_ubyte0_e32 v199, v199
	v_mul_f32_e32 v199, v174, v199
	ds_bpermute_b32 v216, v213, v44
	ds_bpermute_b32 v217, v213, v45
	ds_bpermute_b32 v218, v213, v46
	ds_bpermute_b32 v219, v213, v47
	v_mul_f32_e32 v220, 0x3e22f983, v199
	v_mul_f32_e32 v221, 0x3d4e2601, v199
	v_mul_f32_e32 v222, 0x3c826136, v199
	v_mul_f32_e32 v223, 0x3ba4eb34, v199
	v_cos_f32_e32 v224, v220
	v_cos_f32_e32 v225, v221
	v_cos_f32_e32 v226, v222
	v_cos_f32_e32 v227, v223
	v_sin_f32_e32 v220, v220
	v_sin_f32_e32 v221, v221
	v_sin_f32_e32 v222, v222
	v_sin_f32_e32 v223, v223
	s_waitcnt lgkmcnt(0)
	v_pk_mul_f32 v[216:217], v[216:217], v[220:221]
	v_pk_mul_f32 v[218:219], v[218:219], v[222:223]
	v_pk_fma_f32 v[44:45], v[44:45], v[224:225], v[216:217]
	v_pk_fma_f32 v[46:47], v[46:47], v[226:227], v[218:219]
	ds_bpermute_b32 v216, v213, v40
	ds_bpermute_b32 v217, v213, v41
	ds_bpermute_b32 v218, v213, v42
	ds_bpermute_b32 v219, v213, v43
	v_mul_f32_e32 v220, 0x3ad09b8a, v199
	v_mul_f32_e32 v221, 0x3a03ef5d, v199
	v_mul_f32_e32 v222, 0x3926e2d4, v199
	v_mul_f32_e32 v223, 0x38531894, v199
	v_cos_f32_e32 v224, v220
	v_cos_f32_e32 v225, v221
	v_cos_f32_e32 v226, v222
	v_cos_f32_e32 v227, v223
	v_sin_f32_e32 v220, v220
	v_sin_f32_e32 v221, v221
	v_sin_f32_e32 v222, v222
	v_sin_f32_e32 v223, v223
	s_waitcnt lgkmcnt(0)
	v_pk_mul_f32 v[216:217], v[216:217], v[220:221]
	v_pk_mul_f32 v[218:219], v[218:219], v[222:223]
	v_pk_fma_f32 v[40:41], v[40:41], v[224:225], v[216:217]
	v_pk_fma_f32 v[42:43], v[42:43], v[226:227], v[218:219]
.Lq2_110:
	v_cvt_pk_bf16_f32 v44, v44, v45
	v_cvt_pk_bf16_f32 v45, v46, v47
	v_cvt_pk_bf16_f32 v46, v40, v41
	v_cvt_pk_bf16_f32 v47, v42, v43
	global_store_dwordx4 v197, v[44:47], s[16:17]
	v_pk_mul_f32 v[36:37], v[36:37], v[198:199] op_sel_hi:[1,0]
	v_pk_mul_f32 v[38:39], v[38:39], v[198:199] op_sel_hi:[1,0]
	v_pk_mul_f32 v[32:33], v[32:33], v[198:199] op_sel_hi:[1,0]
	v_pk_mul_f32 v[34:35], v[34:35], v[198:199] op_sel_hi:[1,0]
	s_cmp_eq_u32 s62, 0
	s_cbranch_scc1 .Lq2_111
	v_mov_b32_e32 v199, s55
	v_cndmask_b32_e64 v199, v202, v199, s[10:11]
	v_cvt_f32_ubyte0_e32 v199, v199
	v_mul_f32_e32 v199, v174, v199
	ds_bpermute_b32 v216, v213, v36
	ds_bpermute_b32 v217, v213, v37
	ds_bpermute_b32 v218, v213, v38
	ds_bpermute_b32 v219, v213, v39
	v_mul_f32_e32 v220, 0x3e22f983, v199
	v_mul_f32_e32 v221, 0x3d4e2601, v199
	v_mul_f32_e32 v222, 0x3c826136, v199
	v_mul_f32_e32 v223, 0x3ba4eb34, v199
	v_cos_f32_e32 v224, v220
	v_cos_f32_e32 v225, v221
	v_cos_f32_e32 v226, v222
	v_cos_f32_e32 v227, v223
	v_sin_f32_e32 v220, v220
	v_sin_f32_e32 v221, v221
	v_sin_f32_e32 v222, v222
	v_sin_f32_e32 v223, v223
	s_waitcnt lgkmcnt(0)
	v_pk_mul_f32 v[216:217], v[216:217], v[220:221]
	v_pk_mul_f32 v[218:219], v[218:219], v[222:223]
	v_pk_fma_f32 v[36:37], v[36:37], v[224:225], v[216:217]
	v_pk_fma_f32 v[38:39], v[38:39], v[226:227], v[218:219]
	ds_bpermute_b32 v216, v213, v32
	ds_bpermute_b32 v217, v213, v33
	ds_bpermute_b32 v218, v213, v34
	ds_bpermute_b32 v219, v213, v35
	v_mul_f32_e32 v220, 0x3ad09b8a, v199
	v_mul_f32_e32 v221, 0x3a03ef5d, v199
	v_mul_f32_e32 v222, 0x3926e2d4, v199
	v_mul_f32_e32 v223, 0x38531894, v199
	v_cos_f32_e32 v224, v220
	v_cos_f32_e32 v225, v221
	v_cos_f32_e32 v226, v222
	v_cos_f32_e32 v227, v223
	v_sin_f32_e32 v220, v220
	v_sin_f32_e32 v221, v221
	v_sin_f32_e32 v222, v222
	v_sin_f32_e32 v223, v223
	s_waitcnt lgkmcnt(0)
	v_pk_mul_f32 v[216:217], v[216:217], v[220:221]
	v_pk_mul_f32 v[218:219], v[218:219], v[222:223]
	v_pk_fma_f32 v[32:33], v[32:33], v[224:225], v[216:217]
	v_pk_fma_f32 v[34:35], v[34:35], v[226:227], v[218:219]
.Lq2_111:
	v_cvt_pk_bf16_f32 v36, v36, v37
	v_cvt_pk_bf16_f32 v37, v38, v39
	v_cvt_pk_bf16_f32 v38, v32, v33
	v_cvt_pk_bf16_f32 v39, v34, v35
	global_store_dwordx4 v197, v[36:39], s[16:17] offset:256
	v_add_u32_e32 v197, 0x3c000, v211
	v_pk_mul_f32 v[28:29], v[28:29], v[210:211] op_sel_hi:[1,0]
	v_pk_mul_f32 v[30:31], v[30:31], v[210:211] op_sel_hi:[1,0]
	v_pk_mul_f32 v[24:25], v[24:25], v[210:211] op_sel_hi:[1,0]
	v_pk_mul_f32 v[26:27], v[26:27], v[210:211] op_sel_hi:[1,0]
	s_cmp_eq_u32 s61, 0
	s_cbranch_scc1 .Lq2_120
	v_mov_b32_e32 v199, s55
	v_cndmask_b32_e64 v199, v203, v199, s[10:11]
	v_cvt_f32_ubyte0_e32 v199, v199
	v_mul_f32_e32 v199, v174, v199
	ds_bpermute_b32 v216, v213, v28
	ds_bpermute_b32 v217, v213, v29
	ds_bpermute_b32 v218, v213, v30
	ds_bpermute_b32 v219, v213, v31
	v_mul_f32_e32 v220, 0x3e22f983, v199
	v_mul_f32_e32 v221, 0x3d4e2601, v199
	v_mul_f32_e32 v222, 0x3c826136, v199
	v_mul_f32_e32 v223, 0x3ba4eb34, v199
	v_cos_f32_e32 v224, v220
	v_cos_f32_e32 v225, v221
	v_cos_f32_e32 v226, v222
	v_cos_f32_e32 v227, v223
	v_sin_f32_e32 v220, v220
	v_sin_f32_e32 v221, v221
	v_sin_f32_e32 v222, v222
	v_sin_f32_e32 v223, v223
	s_waitcnt lgkmcnt(0)
	v_pk_mul_f32 v[216:217], v[216:217], v[220:221]
	v_pk_mul_f32 v[218:219], v[218:219], v[222:223]
	v_pk_fma_f32 v[28:29], v[28:29], v[224:225], v[216:217]
	v_pk_fma_f32 v[30:31], v[30:31], v[226:227], v[218:219]
	ds_bpermute_b32 v216, v213, v24
	ds_bpermute_b32 v217, v213, v25
	ds_bpermute_b32 v218, v213, v26
	ds_bpermute_b32 v219, v213, v27
	v_mul_f32_e32 v220, 0x3ad09b8a, v199
	v_mul_f32_e32 v221, 0x3a03ef5d, v199
	v_mul_f32_e32 v222, 0x3926e2d4, v199
	v_mul_f32_e32 v223, 0x38531894, v199
	v_cos_f32_e32 v224, v220
	v_cos_f32_e32 v225, v221
	v_cos_f32_e32 v226, v222
	v_cos_f32_e32 v227, v223
	v_sin_f32_e32 v220, v220
	v_sin_f32_e32 v221, v221
	v_sin_f32_e32 v222, v222
	v_sin_f32_e32 v223, v223
	s_waitcnt lgkmcnt(0)
	v_pk_mul_f32 v[216:217], v[216:217], v[220:221]
	v_pk_mul_f32 v[218:219], v[218:219], v[222:223]
	v_pk_fma_f32 v[24:25], v[24:25], v[224:225], v[216:217]
	v_pk_fma_f32 v[26:27], v[26:27], v[226:227], v[218:219]
.Lq2_120:
	v_cvt_pk_bf16_f32 v28, v28, v29
	v_cvt_pk_bf16_f32 v29, v30, v31
	v_cvt_pk_bf16_f32 v30, v24, v25
	v_cvt_pk_bf16_f32 v31, v26, v27
	global_store_dwordx4 v197, v[28:31], s[16:17]
	v_pk_mul_f32 v[20:21], v[20:21], v[210:211] op_sel_hi:[1,0]
	v_pk_mul_f32 v[22:23], v[22:23], v[210:211] op_sel_hi:[1,0]
	v_pk_mul_f32 v[16:17], v[16:17], v[210:211] op_sel_hi:[1,0]
	v_pk_mul_f32 v[18:19], v[18:19], v[210:211] op_sel_hi:[1,0]
	s_cmp_eq_u32 s62, 0
	s_cbranch_scc1 .Lq2_121
	v_mov_b32_e32 v199, s55
	v_cndmask_b32_e64 v199, v203, v199, s[10:11]
	v_cvt_f32_ubyte0_e32 v199, v199
	v_mul_f32_e32 v199, v174, v199
	ds_bpermute_b32 v216, v213, v20
	ds_bpermute_b32 v217, v213, v21
	ds_bpermute_b32 v218, v213, v22
	ds_bpermute_b32 v219, v213, v23
	v_mul_f32_e32 v220, 0x3e22f983, v199
	v_mul_f32_e32 v221, 0x3d4e2601, v199
	v_mul_f32_e32 v222, 0x3c826136, v199
	v_mul_f32_e32 v223, 0x3ba4eb34, v199
	v_cos_f32_e32 v224, v220
	v_cos_f32_e32 v225, v221
	v_cos_f32_e32 v226, v222
	v_cos_f32_e32 v227, v223
	v_sin_f32_e32 v220, v220
	v_sin_f32_e32 v221, v221
	v_sin_f32_e32 v222, v222
	v_sin_f32_e32 v223, v223
	s_waitcnt lgkmcnt(0)
	v_pk_mul_f32 v[216:217], v[216:217], v[220:221]
	v_pk_mul_f32 v[218:219], v[218:219], v[222:223]
	v_pk_fma_f32 v[20:21], v[20:21], v[224:225], v[216:217]
	v_pk_fma_f32 v[22:23], v[22:23], v[226:227], v[218:219]
	ds_bpermute_b32 v216, v213, v16
	ds_bpermute_b32 v217, v213, v17
	ds_bpermute_b32 v218, v213, v18
	ds_bpermute_b32 v219, v213, v19
	v_mul_f32_e32 v220, 0x3ad09b8a, v199
	v_mul_f32_e32 v221, 0x3a03ef5d, v199
	v_mul_f32_e32 v222, 0x3926e2d4, v199
	v_mul_f32_e32 v223, 0x38531894, v199
	v_cos_f32_e32 v224, v220
	v_cos_f32_e32 v225, v221
	v_cos_f32_e32 v226, v222
	v_cos_f32_e32 v227, v223
	v_sin_f32_e32 v220, v220
	v_sin_f32_e32 v221, v221
	v_sin_f32_e32 v222, v222
	v_sin_f32_e32 v223, v223
	s_waitcnt lgkmcnt(0)
	v_pk_mul_f32 v[216:217], v[216:217], v[220:221]
	v_pk_mul_f32 v[218:219], v[218:219], v[222:223]
	v_pk_fma_f32 v[16:17], v[16:17], v[224:225], v[216:217]
	v_pk_fma_f32 v[18:19], v[18:19], v[226:227], v[218:219]
.Lq2_121:
	v_cvt_pk_bf16_f32 v20, v20, v21
	v_cvt_pk_bf16_f32 v21, v22, v23
	v_cvt_pk_bf16_f32 v22, v16, v17
	v_cvt_pk_bf16_f32 v23, v18, v19
	global_store_dwordx4 v197, v[20:23], s[16:17] offset:256
	v_add_u32_e32 v197, 0x42000, v211
	v_pk_mul_f32 v[12:13], v[12:13], v[212:213] op_sel_hi:[1,0]
	v_pk_mul_f32 v[14:15], v[14:15], v[212:213] op_sel_hi:[1,0]
	v_pk_mul_f32 v[8:9], v[8:9], v[212:213] op_sel_hi:[1,0]
	v_pk_mul_f32 v[10:11], v[10:11], v[212:213] op_sel_hi:[1,0]
	s_cmp_eq_u32 s61, 0
	s_cbranch_scc1 .Lq2_130
	v_mov_b32_e32 v199, s55
	v_cndmask_b32_e64 v199, v204, v199, s[10:11]
	v_cvt_f32_ubyte0_e32 v199, v199
	v_mul_f32_e32 v199, v174, v199
	ds_bpermute_b32 v216, v213, v12
	ds_bpermute_b32 v217, v213, v13
	ds_bpermute_b32 v218, v213, v14
	ds_bpermute_b32 v219, v213, v15
	v_mul_f32_e32 v220, 0x3e22f983, v199
	v_mul_f32_e32 v221, 0x3d4e2601, v199
	v_mul_f32_e32 v222, 0x3c826136, v199
	v_mul_f32_e32 v223, 0x3ba4eb34, v199
	v_cos_f32_e32 v224, v220
	v_cos_f32_e32 v225, v221
	v_cos_f32_e32 v226, v222
	v_cos_f32_e32 v227, v223
	v_sin_f32_e32 v220, v220
	v_sin_f32_e32 v221, v221
	v_sin_f32_e32 v222, v222
	v_sin_f32_e32 v223, v223
	s_waitcnt lgkmcnt(0)
	v_pk_mul_f32 v[216:217], v[216:217], v[220:221]
	v_pk_mul_f32 v[218:219], v[218:219], v[222:223]
	v_pk_fma_f32 v[12:13], v[12:13], v[224:225], v[216:217]
	v_pk_fma_f32 v[14:15], v[14:15], v[226:227], v[218:219]
	ds_bpermute_b32 v216, v213, v8
	ds_bpermute_b32 v217, v213, v9
	ds_bpermute_b32 v218, v213, v10
	ds_bpermute_b32 v219, v213, v11
	v_mul_f32_e32 v220, 0x3ad09b8a, v199
	v_mul_f32_e32 v221, 0x3a03ef5d, v199
	v_mul_f32_e32 v222, 0x3926e2d4, v199
	v_mul_f32_e32 v223, 0x38531894, v199
	v_cos_f32_e32 v224, v220
	v_cos_f32_e32 v225, v221
	v_cos_f32_e32 v226, v222
	v_cos_f32_e32 v227, v223
	v_sin_f32_e32 v220, v220
	v_sin_f32_e32 v221, v221
	v_sin_f32_e32 v222, v222
	v_sin_f32_e32 v223, v223
	s_waitcnt lgkmcnt(0)
	v_pk_mul_f32 v[216:217], v[216:217], v[220:221]
	v_pk_mul_f32 v[218:219], v[218:219], v[222:223]
	v_pk_fma_f32 v[8:9], v[8:9], v[224:225], v[216:217]
	v_pk_fma_f32 v[10:11], v[10:11], v[226:227], v[218:219]
.Lq2_130:
	v_cvt_pk_bf16_f32 v12, v12, v13
	v_cvt_pk_bf16_f32 v13, v14, v15
	v_cvt_pk_bf16_f32 v14, v8, v9
	v_cvt_pk_bf16_f32 v15, v10, v11
	global_store_dwordx4 v197, v[12:15], s[16:17]
	v_pk_mul_f32 v[4:5], v[4:5], v[212:213] op_sel_hi:[1,0]
	v_pk_mul_f32 v[6:7], v[6:7], v[212:213] op_sel_hi:[1,0]
	v_pk_mul_f32 v[0:1], v[0:1], v[212:213] op_sel_hi:[1,0]
	v_pk_mul_f32 v[2:3], v[2:3], v[212:213] op_sel_hi:[1,0]
	s_cmp_eq_u32 s62, 0
	s_cbranch_scc1 .Lq2_131
	v_mov_b32_e32 v199, s55
	v_cndmask_b32_e64 v199, v204, v199, s[10:11]
	v_cvt_f32_ubyte0_e32 v199, v199
	v_mul_f32_e32 v199, v174, v199
	ds_bpermute_b32 v216, v213, v4
	ds_bpermute_b32 v217, v213, v5
	ds_bpermute_b32 v218, v213, v6
	ds_bpermute_b32 v219, v213, v7
	v_mul_f32_e32 v220, 0x3e22f983, v199
	v_mul_f32_e32 v221, 0x3d4e2601, v199
	v_mul_f32_e32 v222, 0x3c826136, v199
	v_mul_f32_e32 v223, 0x3ba4eb34, v199
	v_cos_f32_e32 v224, v220
	v_cos_f32_e32 v225, v221
	v_cos_f32_e32 v226, v222
	v_cos_f32_e32 v227, v223
	v_sin_f32_e32 v220, v220
	v_sin_f32_e32 v221, v221
	v_sin_f32_e32 v222, v222
	v_sin_f32_e32 v223, v223
	s_waitcnt lgkmcnt(0)
	v_pk_mul_f32 v[216:217], v[216:217], v[220:221]
	v_pk_mul_f32 v[218:219], v[218:219], v[222:223]
	v_pk_fma_f32 v[4:5], v[4:5], v[224:225], v[216:217]
	v_pk_fma_f32 v[6:7], v[6:7], v[226:227], v[218:219]
	ds_bpermute_b32 v216, v213, v0
	ds_bpermute_b32 v217, v213, v1
	ds_bpermute_b32 v218, v213, v2
	ds_bpermute_b32 v219, v213, v3
	v_mul_f32_e32 v220, 0x3ad09b8a, v199
	v_mul_f32_e32 v221, 0x3a03ef5d, v199
	v_mul_f32_e32 v222, 0x3926e2d4, v199
	v_mul_f32_e32 v223, 0x38531894, v199
	v_cos_f32_e32 v224, v220
	v_cos_f32_e32 v225, v221
	v_cos_f32_e32 v226, v222
	v_cos_f32_e32 v227, v223
	v_sin_f32_e32 v220, v220
	v_sin_f32_e32 v221, v221
	v_sin_f32_e32 v222, v222
	v_sin_f32_e32 v223, v223
	s_waitcnt lgkmcnt(0)
	v_pk_mul_f32 v[216:217], v[216:217], v[220:221]
	v_pk_mul_f32 v[218:219], v[218:219], v[222:223]
	v_pk_fma_f32 v[0:1], v[0:1], v[224:225], v[216:217]
	v_pk_fma_f32 v[2:3], v[2:3], v[226:227], v[218:219]
.Lq2_131:
	v_cvt_pk_bf16_f32 v4, v4, v5
	v_cvt_pk_bf16_f32 v5, v6, v7
	v_cvt_pk_bf16_f32 v6, v0, v1
	v_cvt_pk_bf16_f32 v7, v2, v3
	global_store_dwordx4 v197, v[4:7], s[16:17] offset:256
	s_and_b64 vcc, exec, s[4:5]
	s_mov_b64 s[2:3], -1
	s_cbranch_vccnz .LBB0_826
	s_andn2_b64 vcc, exec, s[14:15]
	s_cbranch_vccnz .LBB0_825
	s_barrier
	s_branch .LBB0_825
